# speedup vs baseline: 1.0015x; 1.0015x over previous
.LBB0_12:
	s_load_dwordx16 s[4:19], s[0:1], 0x0
	v_readlane_b32 s0, v242, 0
	s_lshr_b32 s0, s0, 6
	s_bfe_u32 s92, s2, 0x20001
	v_writelane_b32 v242, s0, 1
	s_lshr_b32 s84, s85, 2
	s_lshr_b32 s0, s85, 3
	s_bitcmp1_b32 s2, 0
	s_cselect_b32 s33, s0, 0
	s_lshr_b32 s0, s2, 3
	s_add_i32 s33, s33, s0
	s_mul_i32 s90, s92, 0xc000000
	s_add_u32 s0, s50, s90
	s_addc_u32 s1, s51, 0
	s_add_u32 s54, s0, 0xc000000
	s_addc_u32 s55, s1, 0
	s_lshl_b32 s91, s92, 26
	s_lshl_b32 s0, s92, 15
	s_add_u32 s0, s50, s0
	s_addc_u32 s1, s51, 0
	s_add_u32 s87, s0, 0x3c010000
	s_addc_u32 s88, s1, 0
	s_cmp_lt_i32 s52, 1
	s_cselect_b64 s[0:1], -1, 0
	s_cmp_gt_i32 s53, 0
	s_cselect_b64 s[20:21], -1, 0
	s_and_b64 s[0:1], s[0:1], s[20:21]
	s_andn2_b64 vcc, exec, s[0:1]
	s_cbranch_vccnz .LBB0_83
	s_cmpk_gt_i32 s2, 0x5fff
	s_cbranch_scc1 .LBB0_64
	s_add_u32 s0, s50, 0xa000000
	s_addc_u32 s1, s51, 0
	s_add_u32 s20, s50, 0x8000000
	s_addc_u32 s21, s51, 0
	s_add_u32 s22, s50, 0x6000000
	s_addc_u32 s23, s51, 0
	s_add_u32 s24, s50, 0x4000000
	s_addc_u32 s25, s51, 0
	s_add_u32 s26, s50, 0x3800000
	s_addc_u32 s27, s51, 0
	s_add_u32 s28, s50, 0x3000000
	s_addc_u32 s29, s51, 0
	s_add_u32 s30, s50, 0x2800000
	s_addc_u32 s31, s51, 0
	s_add_u32 s34, s50, 0x2000000
	s_addc_u32 s35, s51, 0
	s_add_u32 s56, s50, 0x1800000
	s_addc_u32 s57, s51, 0
	s_add_u32 s58, s50, 0x1000000
	v_readlane_b32 s3, v242, 0
	s_addc_u32 s59, s51, 0
	s_andn2_b32 s3, s3, 63
	s_add_u32 s60, s46, 0x4000000
	s_addc_u32 s61, s47, 0
	s_add_u32 s62, s44, 0x4000000
	s_addc_u32 s63, s45, 0
	s_add_u32 s64, s40, 0x2000
	s_addc_u32 s65, s41, 0
	s_add_u32 s66, s36, 0x2000
	s_addc_u32 s67, s37, 0
	s_movk_i32 s86, 0x104
	s_movk_i32 s93, 0x80
	v_mov_b32_e32 v5, 0
	s_mov_b32 s98, 0
	s_branch .LBB0_16
.LBB0_15:
	s_xor_b32 s98, s98, 0x4200
	v_ashrrev_i32_e32 v4, 5, v6
	v_ashrrev_i32_e32 v8, 4, v7
	v_ashrrev_i32_e32 v6, 31, v4
	v_ashrrev_i32_e32 v9, 31, v8
	v_mul_lo_u32 v6, s70, v6
	v_mad_u64_u32 v[8:9], s[72:73], s70, v4, v[8:9]
	v_mul_lo_u32 v4, s71, v4
	v_add3_u32 v9, v4, v9, v6
	v_lshlrev_b64 v[8:9], 10, v[8:9]
	v_lshlrev_b32_e32 v4, 6, v7
	v_and_b32_e32 v10, 24, v12
	v_lshl_add_u64 v[8:9], s[68:69], 0, v[8:9]
	v_and_b32_e32 v4, 0x3c0, v4
	v_lshl_add_u64 v[6:7], v[8:9], 0, v[4:5]
	v_lshlrev_b32_e32 v4, 1, v10
	s_add_i32 s2, s2, s85
	v_lshl_add_u64 v[6:7], v[6:7], 0, v[4:5]
	s_cmpk_gt_i32 s2, 0x5fff
	global_store_dwordx4 v[6:7], v[0:3], off
	s_cbranch_scc1 .LBB0_64

.LBB0_60:
	s_mul_i32 s83, s83, s95
	s_sub_i32 s72, s94, s83
	s_lshl_b32 s83, s72, 6
	v_add_u32_e32 v2, s89, v1
	v_ashrrev_i32_e32 v1, 4, v4
	v_add_u32_e32 v10, s83, v1
	v_ashrrev_i32_e32 v6, 31, v10
	v_ashrrev_i32_e32 v3, 31, v2
	v_mul_lo_u32 v8, s78, v6
	v_mul_lo_u32 v9, s79, v10
	v_mad_u64_u32 v[6:7], s[72:73], s78, v10, 0
	v_add_u32_e32 v10, 32, v10
	v_lshl_add_u64 v[2:3], v[2:3], 2, s[76:77]
	v_add3_u32 v7, v7, v8, v9
	v_ashrrev_i32_e32 v11, 31, v10
	v_lshl_add_u64 v[6:7], v[6:7], 2, v[2:3]
	v_mul_lo_u32 v12, s78, v11
	v_mul_lo_u32 v13, s79, v10
	v_mad_u64_u32 v[10:11], s[72:73], s78, v10, 0
	global_load_dwordx4 v[6:9], v[6:7], off nt
	v_add3_u32 v11, v11, v12, v13
	v_lshl_add_u64 v[2:3], v[10:11], 2, v[2:3]
	global_load_dwordx4 v[14:17], v[2:3], off nt
	v_lshlrev_b32_e32 v12, 3, v4
	v_mul_lo_u32 v1, v1, s86
	v_and_b32_e32 v18, 56, v12
	v_ashrrev_i32_e32 v13, 3, v4
	v_lshl_add_u32 v0, v0, 2, v1
	v_add_u32_e32 v0, s98, v0
	v_mul_u32_u24_e32 v1, 0x104, v18
	v_lshl_add_u32 v10, v13, 2, v1
	v_add_u32_e32 v10, s98, v10
	v_add_u32_e32 v2, 0x2080, v0
	v_add_u32_e32 v3, 0x2088, v0
	v_add_u32_e32 v11, 0x400, v10
	s_cmp_eq_u64 s[74:75], 0
	s_waitcnt vmcnt(1)
	ds_write2_b32 v0, v6, v7 offset1:1
	ds_write2_b32 v0, v8, v9 offset0:2 offset1:3
	s_waitcnt vmcnt(0)
	ds_write2_b32 v2, v14, v15 offset1:1
	ds_write2_b32 v3, v16, v17 offset1:1
	s_waitcnt lgkmcnt(0)
	s_barrier
	ds_read2_b32 v[0:1], v10 offset1:65
	ds_read2_b32 v[8:9], v10 offset0:130 offset1:195
	ds_read2_b32 v[2:3], v11 offset0:4 offset1:69
	ds_read2_b32 v[10:11], v11 offset0:134 offset1:199
	v_or_b32_e32 v6, s83, v18
	s_cbranch_scc1 .LBB0_62
	v_ashrrev_i32_e32 v7, 31, v6
	v_lshl_add_u64 v[18:19], v[6:7], 2, s[74:75]
	global_load_dwordx4 v[14:17], v[18:19], off
	s_nop 0
	global_load_dwordx4 v[18:21], v[18:19], off offset:16
	s_waitcnt vmcnt(1) lgkmcnt(3)
	v_pk_mul_f32 v[0:1], v[0:1], v[14:15]
	s_waitcnt lgkmcnt(2)
	v_pk_mul_f32 v[8:9], v[8:9], v[16:17]
	s_waitcnt vmcnt(0) lgkmcnt(1)
	v_pk_mul_f32 v[2:3], v[2:3], v[18:19]
	s_waitcnt lgkmcnt(0)
	v_pk_mul_f32 v[10:11], v[10:11], v[20:21]
